# v11 + HGRN2 output unit: each chunk's two gate-row loads issued in the chunk top (fresh registers) instead of right before use
# baseline (speedup 1.0000x reference)
; #define LAS __attribute__((address_space(3)))
; #define LDS_SYNC() do { asm volatile("s_waitcnt lgkmcnt(0)" ::: "memory"); __builtin_amdgcn_s_barrier(); asm volatile("" ::: "memory"); } while (0)
; __device__ __forceinline__ unsigned pk2(float lo, float hi) { return pg8::cvt_pk_bf16(lo, hi); }
; template <bool OUT>
; __device__ __forceinline__ void hgrn_unit(int unit, LAS unsigned char* lds, const float* HLF, const bf16* HQ, const bf16* HV, const bf16* HG, bf16* MIX, float* UBUF, float* DTOT, const float* SST, gu32* rdy4 = nullptr) {
;     ...
;             const int ti = wid & 1, vi = wid >> 1;
; #pragma unroll
;             for (int r = 0; r < 16; ++r) oacc[r] = 0.f;
; #pragma unroll
;             for (int ks = 0; ks < 4; ++ks) { const bf16x8 a = *(const LAS bf16x8*)(PP + (32 * ti + r32) * 72 + 16 * ks + 8 * hi), bb = *(const LAS bf16x8*)(VT + (32 * vi + r32) * 72 + 16 * ks + 8 * hi); oacc = MFMA32(a, bb, oacc); }
; #pragma unroll
;             for (int ks = 0; ks < 8; ++ks) { const bf16x8 a = *(const LAS bf16x8*)(QT + (32 * ti + r32) * 136 + 16 * ks + 8 * hi), bb = *(const LAS bf16x8*)(ST + (32 * vi + r32) * 136 + 16 * ks + 8 * hi); oacc = MFMA32(a, bb, oacc); }
;         }
;         {
;             float dk[16];
; #pragma unroll
;             for (int r = 0; r < 16; ++r) dk[r] = DEC[32 * ki + crow(r, hi)];
; #pragma unroll
;             for (int j = 0; j < 2; ++j)
; #pragma unroll
;                 for (int r = 0; r < 16; ++r) S[j][r] *= dk[r];
; #pragma unroll
;             for (int ks = 0; ks < 4; ++ks) { const bf16x8 a = *(const LAS bf16x8*)(KET + (32 * ki + r32) * 72 + 16 * ks + 8 * hi);
; #pragma unroll
;                 for (int j = 0; j < 2; ++j) { const bf16x8 bb = *(const LAS bf16x8*)(VT + (32 * (vi0 + j) + r32) * 72 + 16 * ks + 8 * hi); S[j] = MFMA32(a, bb, S[j]); } }
;         }
;         if (OUT) {
;             LDS_SYNC();
;             const int ti = wid & 1, vi = wid >> 1;
; #pragma unroll
;             for (int r = 0; r < 16; ++r) OS[(32 * ti + crow(r, hi)) * 132 + 32 * vi + r32] = oacc[r];
; #pragma unroll
;             for (int j = 0; j < 2; ++j)
; #pragma unroll
;                 for (int g = 0; g < 4; ++g) *(LAS v2u*)(ST + (32 * (vi0 + j) + r32) * 136 + 32 * ki + 8 * g + 4 * hi) = (v2u){pk2(S[j][4 * g], S[j][4 * g + 1]), pk2(S[j][4 * g + 2], S[j][4 * g + 3])};
;             LDS_SYNC();
.LBB0_585:
	s_waitcnt lgkmcnt(0)
	s_barrier
	ds_read_b128 v[34:37], v86
	ds_read_b128 v[38:41], v87 offset:53248
	ds_read_b128 v[98:101], v86 offset:32
	ds_read_b128 v[102:105], v87 offset:53280
	s_waitcnt lgkmcnt(2)
	v_mfma_f32_32x32x16_bf16 v[34:49], v[34:37], v[38:41], 0
	s_waitcnt lgkmcnt(0)
	v_mfma_f32_32x32x16_bf16 v[34:49], v[98:101], v[102:105], v[34:49]
	ds_read_b128 v[98:101], v86 offset:64
	ds_read_b128 v[102:105], v87 offset:53312
	ds_read_b128 v[106:109], v86 offset:96
	ds_read_b128 v[110:113], v87 offset:53344
	s_waitcnt lgkmcnt(2)
	v_mfma_f32_32x32x16_bf16 v[34:49], v[98:101], v[102:105], v[34:49]
	s_waitcnt lgkmcnt(0)
	v_mfma_f32_32x32x16_bf16 v[34:49], v[106:109], v[110:113], v[34:49]
	ds_read_b128 v[98:101], v88
	ds_read_b128 v[102:105], v89
	ds_read_b128 v[106:109], v88 offset:32
	ds_read_b128 v[110:113], v89 offset:32
	s_waitcnt lgkmcnt(2)
	v_mfma_f32_32x32x16_bf16 v[34:49], v[98:101], v[102:105], v[34:49]
	s_waitcnt lgkmcnt(0)
	v_mfma_f32_32x32x16_bf16 v[34:49], v[106:109], v[110:113], v[34:49]
	ds_read_b128 v[98:101], v88 offset:64
	ds_read_b128 v[102:105], v89 offset:64
	ds_read_b128 v[106:109], v88 offset:96
	ds_read_b128 v[110:113], v89 offset:96
	s_waitcnt lgkmcnt(2)
	v_mfma_f32_32x32x16_bf16 v[34:49], v[98:101], v[102:105], v[34:49]
	s_waitcnt lgkmcnt(0)
	v_mfma_f32_32x32x16_bf16 v[34:49], v[106:109], v[110:113], v[34:49]
	ds_read_b128 v[98:101], v88 offset:128
	ds_read_b128 v[102:105], v89 offset:128
	ds_read_b128 v[106:109], v88 offset:160
	ds_read_b128 v[110:113], v89 offset:160
	s_waitcnt lgkmcnt(2)
	v_mfma_f32_32x32x16_bf16 v[34:49], v[98:101], v[102:105], v[34:49]
	ds_read_b128 v[98:101], v88 offset:192
	ds_read_b128 v[102:105], v88 offset:224
	ds_read_b128 v[114:117], v89 offset:192
	ds_read_b128 v[118:121], v89 offset:224
	ds_read_b128 v[122:125], v90
	ds_read_b128 v[126:129], v90 offset:32
	ds_read_b128 v[130:133], v90 offset:64
	ds_read_b128 v[134:137], v90 offset:96
	s_waitcnt lgkmcnt(3)
	v_pk_mul_f32 v[2:3], v[2:3], v[122:123]
	v_pk_mul_f32 v[4:5], v[4:5], v[124:125]
	s_waitcnt lgkmcnt(2)
	v_pk_mul_f32 v[6:7], v[6:7], v[126:127]
	v_pk_mul_f32 v[8:9], v[8:9], v[128:129]
	s_waitcnt lgkmcnt(1)
	v_pk_mul_f32 v[10:11], v[10:11], v[130:131]
	v_mfma_f32_32x32x16_bf16 v[34:49], v[106:109], v[110:113], v[34:49]
	ds_read_b128 v[106:109], v91 offset:34816
	ds_read_b128 v[110:113], v91 offset:34848
	ds_read_b128 v[138:141], v92 offset:53248
	ds_read_b128 v[142:145], v92 offset:53280
	v_mul_f32_e64 v12, v12, v132
	v_mul_f32_e64 v13, v13, v133
	s_waitcnt lgkmcnt(4)
	v_pk_mul_f32 v[14:15], v[14:15], v[134:135]
	v_pk_mul_f32 v[16:17], v[16:17], v[136:137]
	v_pk_mul_f32 v[18:19], v[18:19], v[122:123]
	v_pk_mul_f32 v[20:21], v[20:21], v[124:125]
	v_pk_mul_f32 v[22:23], v[22:23], v[126:127]
	v_mfma_f32_32x32x16_bf16 v[34:49], v[98:101], v[114:117], v[34:49]
	ds_read_b128 v[98:101], v93 offset:53248
	ds_read_b128 v[114:117], v93 offset:53280
	v_mul_f32_e64 v24, v24, v128
	v_mul_f32_e64 v25, v25, v129
	v_mul_f32_e64 v26, v26, v130
	v_mul_f32_e64 v27, v27, v131
	v_pk_mul_f32 v[28:29], v[28:29], v[132:133]
	v_pk_mul_f32 v[30:31], v[30:31], v[134:135]
	v_pk_mul_f32 v[32:33], v[32:33], v[136:137]
	s_waitcnt lgkmcnt(3)
	v_mfma_f32_32x32x16_bf16 v[2:17], v[106:109], v[138:141], v[2:17]
	s_waitcnt lgkmcnt(1)
	v_mfma_f32_32x32x16_bf16 v[18:33], v[106:109], v[98:101], v[18:33]
	v_mfma_f32_32x32x16_bf16 v[2:17], v[110:113], v[142:145], v[2:17]
	s_waitcnt lgkmcnt(0)
	v_mfma_f32_32x32x16_bf16 v[18:33], v[110:113], v[114:117], v[18:33]
	ds_read_b128 v[98:101], v91 offset:34880
	ds_read_b128 v[106:109], v91 offset:34912
	ds_read_b128 v[110:113], v92 offset:53312
	ds_read_b128 v[114:117], v92 offset:53344
	ds_read_b128 v[122:125], v93 offset:53312
	ds_read_b128 v[126:129], v93 offset:53344
	s_waitcnt lgkmcnt(0)
	s_barrier
	s_waitcnt lgkmcnt(3)
	v_mfma_f32_32x32x16_bf16 v[2:17], v[98:101], v[110:113], v[2:17]
	v_mfma_f32_32x32x16_bf16 v[34:49], v[102:105], v[118:121], v[34:49]
	s_waitcnt lgkmcnt(1)
	v_mfma_f32_32x32x16_bf16 v[18:33], v[98:101], v[122:125], v[18:33]
	s_nop 9
	ds_write2_b32 v94, v34, v35 offset1:132
	v_add_u32_e32 v34, 0x400, v94
	ds_write2_b32 v34, v36, v37 offset0:8 offset1:140
	v_add_u32_e32 v34, 0x1000, v94
	ds_write2_b32 v34, v38, v39 offset0:32 offset1:164
	v_add_u32_e32 v34, 0x1400, v94
	ds_write2_b32 v34, v40, v41 offset0:40 offset1:172
	v_mfma_f32_32x32x16_bf16 v[2:17], v[106:109], v[114:117], v[2:17]
	v_add_u32_e32 v34, 0x2000, v94
	ds_write2_b32 v34, v42, v43 offset0:64 offset1:196
	v_add_u32_e32 v34, 0x2400, v94
	ds_write2_b32 v34, v44, v45 offset0:72 offset1:204
	v_add_u32_e32 v34, 0x3000, v94
	ds_write2_b32 v34, v46, v47 offset0:96 offset1:228
	v_add_u32_e32 v34, 0x3400, v94
	s_waitcnt lgkmcnt(7)
	v_mfma_f32_32x32x16_bf16 v[18:33], v[106:109], v[126:129], v[18:33]
	ds_write2_b32 v34, v48, v49 offset0:104 offset1:236
	s_nop 1
	v_cvt_pk_bf16_f32 v34, v2, v3
	v_cvt_pk_bf16_f32 v35, v4, v5
	v_cvt_pk_bf16_f32 v36, v6, v7
	v_cvt_pk_bf16_f32 v37, v8, v9
	ds_write2_b64 v95, v[34:35], v[36:37] offset1:2
	v_cvt_pk_bf16_f32 v34, v10, v11
	v_cvt_pk_bf16_f32 v35, v12, v13
	v_cvt_pk_bf16_f32 v36, v14, v15
	v_cvt_pk_bf16_f32 v37, v16, v17
	ds_write2_b64 v95, v[34:35], v[36:37] offset0:4 offset1:6
	v_cvt_pk_bf16_f32 v34, v18, v19
	v_cvt_pk_bf16_f32 v35, v20, v21
	v_cvt_pk_bf16_f32 v36, v22, v23
	v_cvt_pk_bf16_f32 v37, v24, v25
	v_add_u32_e32 v106, s58, v81
	ds_write2_b64 v96, v[34:35], v[36:37] offset1:2
	v_cvt_pk_bf16_f32 v34, v26, v27
	v_cvt_pk_bf16_f32 v35, v28, v29
	v_cvt_pk_bf16_f32 v36, v30, v31
	v_cvt_pk_bf16_f32 v37, v32, v33
	v_ashrrev_i32_e32 v107, 31, v106
	ds_write2_b64 v96, v[34:35], v[36:37] offset0:4 offset1:6
	v_lshlrev_b64 v[34:35], 10, v[106:107]
	s_waitcnt lgkmcnt(0)
	s_barrier
; __device__ __forceinline__ void store16_wt(void* p, u32x4 v) { asm volatile("global_store_dwordx4 %0, %1, off sc1\n\ts_nop 1" :: "v"(p), "v"(v) : "memory"); }
; #define LAS __attribute__((address_space(3)))
; #define LDS_SYNC() do { asm volatile("s_waitcnt lgkmcnt(0)" ::: "memory"); __builtin_amdgcn_s_barrier(); asm volatile("" ::: "memory"); } while (0)
; __device__ __forceinline__ unsigned pk2(float lo, float hi) { return pg8::cvt_pk_bf16(lo, hi); }
; template <bool OUT>
; __device__ __forceinline__ void hgrn_unit(int unit, LAS unsigned char* lds, const float* HLF, const bf16* HQ, const bf16* HV, const bf16* HG, bf16* MIX, float* UBUF, float* DTOT, const float* SST, gu32* rdy4 = nullptr) {
;     ...
;             const int t = tid >> 3, seg = tid & 7; const int row = row_base + 64 * c + t;
;             f32x4 o4[4]; float ss = 0.f;
; #pragma unroll
;             for (int i = 0; i < 4; ++i) { o4[i] = *(const LAS f32x4*)(OS + t * 132 + 16 * seg + 4 * i); ss += (o4[i][0] * o4[i][0] + o4[i][1] * o4[i][1]) + (o4[i][2] * o4[i][2] + o4[i][3] * o4[i][3]); }
;             ss += __shfl_xor(ss, 1); ss += __shfl_xor(ss, 2); ss += __shfl_xor(ss, 4);
;             const float rstd = rsqrtf(ss * (1.0f / 128.0f) + EPSF);
;             const v4u g0 = *(const v4u*)(HG + (size_t)row * 512 + col0 + 16 * seg), g1 = *(const v4u*)(HG + (size_t)row * 512 + col0 + 16 * seg + 8);
;             const unsigned gw[8] = {g0.x, g0.y, g0.z, g0.w, g1.x, g1.y, g1.z, g1.w}; unsigned ow[8];
; #pragma unroll
;             for (int i = 0; i < 8; ++i) { const float a = o4[i >> 1][2 * (i & 1)] * rstd * __builtin_bit_cast(float, gw[i] << 16), bq = o4[i >> 1][2 * (i & 1) + 1] * rstd * __builtin_bit_cast(float, gw[i] & 0xffff0000u); ow[i] = pk2(a, bq); }
;             pg8::store16_wt(MIX + (size_t)row * 1024 + 512 + col0 + 16 * seg, (v4u){ow[0], ow[1], ow[2], ow[3]}); pg8::store16_wt(MIX + (size_t)row * 1024 + 512 + col0 + 16 * seg + 8, (v4u){ow[4], ow[5], ow[6], ow[7]});
;         }
;         LDS_SYNC();
	v_lshl_add_u64 v[42:43], v[60:61], 0, v[34:35]
	ds_read_b128 v[38:41], v78
	ds_read_b128 v[46:49], v78 offset:16
	ds_read_b128 v[98:101], v78 offset:32
	ds_read_b128 v[102:105], v78 offset:48
	s_add_i32 s58, s58, 64
	s_cmpk_eq_i32 s58, 0x100
	s_waitcnt lgkmcnt(3)
	v_pk_mul_f32 v[108:109], v[40:41], v[40:41]
	v_pk_mul_f32 v[110:111], v[38:39], v[38:39]
	s_waitcnt lgkmcnt(0)
	v_mul_f32_e32 v97, v102, v102
	v_pk_mov_b32 v[112:113], v[110:111], v[108:109] op_sel:[1,0]
	v_mov_b32_e32 v111, v109
	v_pk_add_f32 v[108:109], v[112:113], v[110:111]
	v_pk_mul_f32 v[110:111], v[48:49], v[48:49]
	v_pk_mul_f32 v[112:113], v[46:47], v[46:47]
	v_pk_add_f32 v[108:109], v[108:109], v[108:109] op_sel:[0,1] op_sel_hi:[1,0]
	v_pk_mov_b32 v[114:115], v[112:113], v[110:111] op_sel:[1,0]
	v_mov_b32_e32 v113, v111
	v_pk_add_f32 v[110:111], v[114:115], v[112:113]
	v_mul_f32_e32 v112, v103, v103
	v_pk_add_f32 v[110:111], v[110:111], v[110:111] op_sel:[0,1] op_sel_hi:[1,0]
	v_mov_b32_e32 v109, v97
	v_mov_b32_e32 v111, v112
	v_pk_add_f32 v[108:109], v[108:109], v[110:111]
	v_mul_f32_e32 v110, v99, v99
	v_mul_f32_e32 v113, v104, v104
	v_pk_fma_f32 v[110:111], v[98:99], v[98:99], v[110:111] op_sel_hi:[1,1,0]
	v_mul_f32_e32 v112, v101, v101
	v_mul_f32_e32 v114, v105, v105
	v_mov_b32_e32 v111, v113
	v_pk_fma_f32 v[112:113], v[100:101], v[100:101], v[112:113] op_sel_hi:[1,1,0]
	s_nop 0
	v_mov_b32_e32 v113, v114
	v_pk_add_f32 v[110:111], v[110:111], v[112:113]
	s_nop 0
	v_pk_add_f32 v[108:109], v[108:109], v[110:111]
	s_waitcnt vmcnt(1)
	v_lshlrev_b32_e32 v110, 16, v200
	v_add_f32_e32 v97, v108, v109
	v_and_b32_e32 v109, 64, v80
	v_xor_b32_e32 v108, 1, v80
	v_add_u32_e32 v109, 64, v109
	v_cmp_lt_i32_e32 vcc, v108, v109
	v_and_b32_e32 v111, 0xffff0000, v200
	s_nop 0
	v_cndmask_b32_e32 v108, v80, v108, vcc
	v_lshlrev_b32_e32 v108, 2, v108
	ds_bpermute_b32 v108, v108, v97
	s_waitcnt lgkmcnt(0)
	v_add_f32_e32 v97, v97, v108
	v_xor_b32_e32 v108, 2, v80
	v_cmp_lt_i32_e32 vcc, v108, v109
	s_nop 1
	v_cndmask_b32_e32 v108, v80, v108, vcc
	v_lshlrev_b32_e32 v108, 2, v108
	ds_bpermute_b32 v108, v108, v97
	s_waitcnt lgkmcnt(0)
	v_add_f32_e32 v97, v97, v108
	v_xor_b32_e32 v108, 4, v80
	v_cmp_lt_i32_e32 vcc, v108, v109
	s_nop 1
	v_cndmask_b32_e32 v108, v80, v108, vcc
	v_lshlrev_b32_e32 v108, 2, v108
	ds_bpermute_b32 v108, v108, v97
	s_waitcnt lgkmcnt(0)
	v_add_f32_e32 v97, v97, v108
	v_fmamk_f32 v97, v97, 0x3c000000, v79
	v_mul_f32_e32 v108, 0x4b800000, v97
	v_cmp_gt_f32_e32 vcc, s55, v97
	s_nop 1
	v_cndmask_b32_e32 v97, v97, v108, vcc
	v_rsq_f32_e32 v97, v97
	s_nop 0
	v_mul_f32_e32 v108, 0x45800000, v97
	v_cndmask_b32_e32 v108, v97, v108, vcc
	v_pk_mul_f32 v[38:39], v[38:39], v[108:109] op_sel_hi:[1,0]
	v_pk_mul_f32 v[40:41], v[40:41], v[108:109] op_sel_hi:[1,0]
	v_pk_mul_f32 v[38:39], v[38:39], v[110:111]
	s_nop 0
	v_cvt_pk_bf16_f32 v34, v38, v39
	v_lshlrev_b32_e32 v38, 16, v201
	v_and_b32_e32 v39, 0xffff0000, v201
	v_pk_mul_f32 v[38:39], v[40:41], v[38:39]
	v_lshlrev_b32_e32 v40, 16, v202
	v_cvt_pk_bf16_f32 v35, v38, v39
	v_pk_mul_f32 v[38:39], v[46:47], v[108:109] op_sel_hi:[1,0]
	v_and_b32_e32 v41, 0xffff0000, v202
	v_pk_mul_f32 v[38:39], v[38:39], v[40:41]
	v_lshlrev_b32_e32 v40, 16, v203
	v_cvt_pk_bf16_f32 v36, v38, v39
	v_pk_mul_f32 v[38:39], v[48:49], v[108:109] op_sel_hi:[1,0]
	v_and_b32_e32 v41, 0xffff0000, v203
	v_pk_mul_f32 v[38:39], v[38:39], v[40:41]
	s_waitcnt vmcnt(0)
	v_lshlrev_b32_e32 v40, 16, v204
	v_cvt_pk_bf16_f32 v37, v38, v39
	v_pk_mul_f32 v[38:39], v[98:99], v[108:109] op_sel_hi:[1,0]
	v_and_b32_e32 v41, 0xffff0000, v204
	v_pk_mul_f32 v[38:39], v[38:39], v[40:41]
	v_pk_mul_f32 v[40:41], v[100:101], v[108:109] op_sel_hi:[1,0]
	v_lshlrev_b32_e32 v42, 16, v205
	v_and_b32_e32 v43, 0xffff0000, v205
	v_pk_mul_f32 v[40:41], v[40:41], v[42:43]
	v_cvt_pk_bf16_f32 v38, v38, v39
	v_cvt_pk_bf16_f32 v39, v40, v41
	v_pk_mul_f32 v[40:41], v[102:103], v[108:109] op_sel_hi:[1,0]
	v_lshlrev_b32_e32 v42, 16, v206
	v_and_b32_e32 v43, 0xffff0000, v206
	v_pk_mul_f32 v[40:41], v[40:41], v[42:43]
	v_pk_mul_f32 v[42:43], v[104:105], v[108:109] op_sel_hi:[1,0]
	v_lshlrev_b32_e32 v44, 16, v207
	v_and_b32_e32 v45, 0xffff0000, v207
	v_pk_mul_f32 v[42:43], v[42:43], v[44:45]
	v_cvt_pk_bf16_f32 v40, v40, v41
	v_cvt_pk_bf16_f32 v41, v42, v43
	v_lshlrev_b64 v[42:43], 11, v[106:107]
	v_lshl_add_u64 v[42:43], s[62:63], 0, v[42:43]
	v_lshl_add_u64 v[42:43], v[42:43], 0, s[70:71]
	v_lshl_add_u64 v[42:43], v[42:43], 0, v[52:53]
	v_lshl_add_u64 v[44:45], v[42:43], 0, s[72:73]
	global_store_dwordx4 v[44:45], v[34:37], off sc1
	s_nop 1
	v_lshl_add_u64 v[34:35], v[42:43], 0, s[74:75]
	global_store_dwordx4 v[34:35], v[38:41], off sc1
	s_nop 1
	s_waitcnt lgkmcnt(0)
	s_barrier
	s_cbranch_scc1 .LBB0_596
; template <bool OUT>
; __device__ __forceinline__ void hgrn_unit(int unit, LAS unsigned char* lds, const float* HLF, const bf16* HQ, const bf16* HV, const bf16* HG, bf16* MIX, float* UBUF, float* DTOT, const float* SST, gu32* rdy4 = nullptr) {
;     ...
;     for (int c = 0; c < 4; ++c) {
;         const int rows = row_base + 64 * c + 16 * tq;
;         float cs[16]; unsigned short vv[16], qq[16];
; #pragma unroll
;         for (int i = 0; i < 16; ++i) { cs[i] = HLF[(size_t)(rows + i) * 512 + col0 + kx]; vv[i] = HV[(size_t)(rows + i) * 512 + col0 + kx]; if (OUT) qq[i] = HQ[(size_t)(rows + i) * 512 + col0 + kx]; }
.LBB0_586:
	v_add_u32_e32 v38, s58, v82
	v_add_u32_e32 v36, 1, v38
	v_ashrrev_i32_e32 v37, 31, v36
	v_lshlrev_b64 v[36:37], 9, v[36:37]
	v_or_b32_e32 v36, v36, v58
	v_lshl_add_u64 v[44:45], v[36:37], 2, s[64:65]
	v_lshlrev_b64 v[46:47], 1, v[36:37]
	v_add_u32_e32 v36, 2, v38
	v_ashrrev_i32_e32 v39, 31, v38
	v_ashrrev_i32_e32 v37, 31, v36
	v_lshlrev_b64 v[34:35], 9, v[38:39]
	v_lshlrev_b64 v[36:37], 9, v[36:37]
	v_or_b32_e32 v34, v34, v58
	v_or_b32_e32 v36, v36, v58
	v_lshl_add_u64 v[40:41], v[34:35], 2, s[64:65]
	v_lshlrev_b64 v[34:35], 1, v[34:35]
	v_lshl_add_u64 v[48:49], s[68:69], 0, v[46:47]
	v_lshl_add_u64 v[98:99], v[36:37], 2, s[64:65]
	v_lshlrev_b64 v[36:37], 1, v[36:37]
	v_lshl_add_u64 v[42:43], s[68:69], 0, v[34:35]
	v_lshl_add_u64 v[100:101], s[68:69], 0, v[36:37]
	global_load_dword v120, v[40:41], off
	global_load_ushort v121, v[42:43], off
	global_load_dword v122, v[44:45], off
	global_load_ushort v123, v[48:49], off
	global_load_dword v124, v[98:99], off
	global_load_ushort v125, v[100:101], off
	v_add_u32_e32 v40, 3, v38
	v_add_u32_e32 v48, 4, v38
	v_ashrrev_i32_e32 v41, 31, v40
	v_ashrrev_i32_e32 v49, 31, v48
	v_add_u32_e32 v102, 5, v38
	v_lshlrev_b64 v[40:41], 9, v[40:41]
	v_lshlrev_b64 v[48:49], 9, v[48:49]
	v_ashrrev_i32_e32 v103, 31, v102
	v_or_b32_e32 v40, v40, v58
	v_or_b32_e32 v48, v48, v58
	v_lshlrev_b64 v[102:103], 9, v[102:103]
	v_lshl_add_u64 v[42:43], v[40:41], 2, s[64:65]
	v_lshlrev_b64 v[40:41], 1, v[40:41]
	v_lshl_add_u64 v[98:99], v[48:49], 2, s[64:65]
	v_lshlrev_b64 v[48:49], 1, v[48:49]
	v_or_b32_e32 v102, v102, v58
	v_lshl_add_u64 v[44:45], s[68:69], 0, v[40:41]
	v_lshl_add_u64 v[100:101], s[68:69], 0, v[48:49]
	v_lshl_add_u64 v[104:105], v[102:103], 2, s[64:65]
	global_load_dword v126, v[42:43], off
	global_load_ushort v127, v[44:45], off
	global_load_dword v128, v[98:99], off
	global_load_ushort v129, v[100:101], off
	global_load_dword v130, v[104:105], off
	v_add_u32_e32 v98, 6, v38
	v_add_u32_e32 v104, 7, v38
	v_ashrrev_i32_e32 v99, 31, v98
	v_ashrrev_i32_e32 v105, 31, v104
	v_lshlrev_b64 v[98:99], 9, v[98:99]
	v_lshlrev_b64 v[104:105], 9, v[104:105]
	v_lshlrev_b64 v[42:43], 1, v[102:103]
	v_or_b32_e32 v98, v98, v58
	v_or_b32_e32 v104, v104, v58
	v_lshl_add_u64 v[44:45], s[68:69], 0, v[42:43]
	v_lshl_add_u64 v[100:101], v[98:99], 2, s[64:65]
	v_lshlrev_b64 v[98:99], 1, v[98:99]
	v_lshl_add_u64 v[106:107], v[104:105], 2, s[64:65]
	v_lshlrev_b64 v[104:105], 1, v[104:105]
	v_lshl_add_u64 v[102:103], s[68:69], 0, v[98:99]
	v_lshl_add_u64 v[108:109], s[68:69], 0, v[104:105]
	global_load_ushort v131, v[44:45], off
	global_load_dword v132, v[100:101], off
	global_load_ushort v133, v[102:103], off
	global_load_dword v134, v[106:107], off
	global_load_ushort v135, v[108:109], off
	v_add_u32_e32 v44, 8, v38
	v_add_u32_e32 v106, 9, v38
	v_add_u32_e32 v112, 10, v38
	v_ashrrev_i32_e32 v45, 31, v44
	v_ashrrev_i32_e32 v107, 31, v106
	v_ashrrev_i32_e32 v113, 31, v112
	v_lshlrev_b64 v[44:45], 9, v[44:45]
	v_lshlrev_b64 v[106:107], 9, v[106:107]
	v_lshlrev_b64 v[112:113], 9, v[112:113]
	v_or_b32_e32 v44, v44, v58
	v_or_b32_e32 v106, v106, v58
	v_or_b32_e32 v112, v112, v58
	v_lshl_add_u64 v[100:101], v[44:45], 2, s[64:65]
	v_lshlrev_b64 v[44:45], 1, v[44:45]
	v_lshl_add_u64 v[108:109], v[106:107], 2, s[64:65]
	v_lshlrev_b64 v[106:107], 1, v[106:107]
	v_lshl_add_u64 v[114:115], v[112:113], 2, s[64:65]
	v_lshlrev_b64 v[112:113], 1, v[112:113]
	v_lshl_add_u64 v[102:103], s[68:69], 0, v[44:45]
	v_lshl_add_u64 v[110:111], s[68:69], 0, v[106:107]
	v_lshl_add_u64 v[116:117], s[68:69], 0, v[112:113]
	global_load_dword v136, v[100:101], off
	global_load_ushort v137, v[102:103], off
	global_load_dword v138, v[108:109], off
	global_load_ushort v139, v[110:111], off
	global_load_dword v140, v[114:115], off
	global_load_ushort v141, v[116:117], off
	v_add_u32_e32 v100, 11, v38
	v_ashrrev_i32_e32 v101, 31, v100
	v_add_u32_e32 v110, 12, v38
	v_lshlrev_b64 v[100:101], 9, v[100:101]
	v_ashrrev_i32_e32 v111, 31, v110
	v_or_b32_e32 v100, v100, v58
	v_lshlrev_b64 v[110:111], 9, v[110:111]
	v_lshl_add_u64 v[102:103], v[100:101], 2, s[64:65]
	v_lshlrev_b64 v[100:101], 1, v[100:101]
	v_or_b32_e32 v110, v110, v58
	v_lshl_add_u64 v[108:109], s[68:69], 0, v[100:101]
	v_lshlrev_b64 v[114:115], 1, v[110:111]
	v_lshl_add_u64 v[116:117], s[68:69], 0, v[114:115]
	global_load_ushort v142, v[108:109], off
	global_load_ushort v143, v[116:117], off
	v_add_u32_e32 v108, 13, v38
	v_ashrrev_i32_e32 v109, 31, v108
	v_lshlrev_b64 v[108:109], 9, v[108:109]
	v_or_b32_e32 v108, v108, v58
	v_lshlrev_b64 v[116:117], 1, v[108:109]
	v_lshl_add_u64 v[118:119], s[68:69], 0, v[116:117]
	global_load_ushort v118, v[118:119], off
	v_lshl_add_u64 v[110:111], v[110:111], 2, s[64:65]
	v_lshl_add_u64 v[108:109], v[108:109], 2, s[64:65]
	global_load_dword v119, v[102:103], off
	global_load_dword v144, v[110:111], off
	global_load_dword v145, v[108:109], off
	v_add_u32_e32 v102, 14, v38
	v_ashrrev_i32_e32 v103, 31, v102
	v_add_u32_e32 v38, 15, v38
	v_lshlrev_b64 v[102:103], 9, v[102:103]
	v_ashrrev_i32_e32 v39, 31, v38
	v_or_b32_e32 v102, v102, v58
	v_lshlrev_b64 v[38:39], 9, v[38:39]
	v_lshl_add_u64 v[108:109], v[102:103], 2, s[64:65]
	v_or_b32_e32 v38, v38, v58
	v_lshl_add_u64 v[110:111], v[38:39], 2, s[64:65]
	global_load_dword v146, v[108:109], off
	global_load_dword v97, v[110:111], off
	v_lshlrev_b64 v[102:103], 1, v[102:103]
	v_lshlrev_b64 v[110:111], 1, v[38:39]
	v_lshl_add_u64 v[108:109], s[68:69], 0, v[102:103]
	v_lshl_add_u64 v[38:39], s[68:69], 0, v[110:111]
	global_load_ushort v108, v[108:109], off
	s_nop 0
	global_load_ushort v109, v[38:39], off
	v_lshl_add_u64 v[38:39], s[66:67], 0, v[46:47]
	v_lshl_add_u64 v[34:35], s[66:67], 0, v[34:35]
	global_load_ushort v147, v[38:39], off
	global_load_ushort v148, v[34:35], off
	v_lshl_add_u64 v[46:47], s[66:67], 0, v[36:37]
	v_lshl_add_u64 v[36:37], s[66:67], 0, v[40:41]
	v_lshl_add_u64 v[38:39], s[66:67], 0, v[48:49]
	v_lshl_add_u64 v[40:41], s[66:67], 0, v[104:105]
	s_waitcnt vmcnt(30)
; #define LDS_SYNC() do { asm volatile("s_waitcnt lgkmcnt(0)" ::: "memory"); __builtin_amdgcn_s_barrier(); asm volatile("" ::: "memory"); } while (0)
; __device__ __forceinline__ unsigned f2bf(float f) { unsigned u = __builtin_bit_cast(unsigned, f); return (u + 0x7fffu + ((u >> 16) & 1u)) >> 16; }
; __device__ __forceinline__ unsigned pk2(float lo, float hi) { return pg8::cvt_pk_bf16(lo, hi); }
; __device__ __forceinline__ float ex2(float x) { return __builtin_amdgcn_exp2f(x); }
; template <bool OUT>
; __device__ __forceinline__ void hgrn_unit(int unit, LAS unsigned char* lds, const float* HLF, const bf16* HQ, const bf16* HV, const bf16* HG, bf16* MIX, float* UBUF, float* DTOT, const float* SST, gu32* rdy4 = nullptr) {
;     ...
;         float lf[16];
; #pragma unroll
;         for (int i = 0; i < 16; ++i) { lf[i] = cs[i]; if (i) cs[i] += cs[i - 1]; }
;         TOT[tq * 128 + kx] = cs[15];
;         LDS_SYNC();
;         float off = 0.f, blast = 0.f;
; #pragma unroll
;         for (int q = 0; q < 4; ++q) { const float t = TOT[q * 128 + kx]; if (q < tq) off += t; blast += t; }
;         unsigned kew[8], vtw[8];
; #pragma unroll
;         for (int i = 0; i < 16; i += 2) {
;             float ke[2];
; #pragma unroll
;             for (int e = 0; e < 2; ++e) { const float bi = off + cs[i + e], kk = 1.0f - ex2(lf[i + e] * LOG2E_F); ke[e] = kk * ex2((blast - bi) * LOG2E_F);
;                 if (OUT) { QT[(16 * tq + i + e) * 136 + kx] = (bf16)f2bf(bf2f(qq[i + e]) * ex2(bi * LOG2E_F)); KI[(16 * tq + i + e) * 136 + kx] = (bf16)f2bf(kk * ex2(-bi * LOG2E_F)); } }
;             kew[i >> 1] = pk2(ke[0], ke[1]); vtw[i >> 1] = (unsigned)vv[i] | ((unsigned)vv[i + 1] << 16);
	v_lshl_or_b32 v34, v123, 16, v121
	global_load_ushort v121, v[38:39], off
	global_load_ushort v123, v[36:37], off
	s_waitcnt vmcnt(28)
	v_lshl_or_b32 v35, v127, 16, v125
	v_lshl_add_u64 v[36:37], s[66:67], 0, v[42:43]
	v_lshl_add_u64 v[38:39], s[66:67], 0, v[98:99]
	global_load_ushort v104, v[40:41], off
	global_load_ushort v105, v[38:39], off
	global_load_ushort v125, v[36:37], off
	v_lshl_add_u64 v[40:41], s[66:67], 0, v[106:107]
	v_lshl_add_u64 v[38:39], s[66:67], 0, v[44:45]
	global_load_ushort v106, v[40:41], off
	global_load_ushort v107, v[38:39], off
	v_lshl_add_u64 v[40:41], s[66:67], 0, v[100:101]
	v_lshl_add_u64 v[44:45], s[66:67], 0, v[114:115]
	v_lshl_add_u64 v[48:49], s[66:67], 0, v[110:111]
	v_lshl_add_u64 v[42:43], s[66:67], 0, v[112:113]
	global_load_ushort v112, v[44:45], off
	global_load_ushort v113, v[40:41], off
	v_lshl_add_u64 v[40:41], s[66:67], 0, v[116:117]
	v_lshl_add_u64 v[44:45], s[66:67], 0, v[102:103]
	global_load_ushort v110, v[48:49], off
	global_load_ushort v111, v[44:45], off
	global_load_ushort v114, v[40:41], off
	global_load_ushort v101, v[46:47], off
	v_add_f32_e32 v45, v120, v122
	v_add_f32_e32 v100, v45, v124
	v_add_f32_e32 v102, v100, v126
	s_waitcnt vmcnt(38)
	v_add_f32_e32 v103, v102, v128
	s_waitcnt vmcnt(36)
	v_add_f32_e32 v115, v103, v130
	s_waitcnt vmcnt(34)
	v_add_f32_e32 v116, v115, v132
	s_waitcnt vmcnt(32)
	v_add_f32_e32 v117, v116, v134
	v_lshl_or_b32 v36, v131, 16, v129
	s_waitcnt vmcnt(31)
	v_lshl_or_b32 v37, v135, 16, v133
	global_load_ushort v131, v[42:43], off
	v_mul_f32_e32 v44, 0x3fb8aa3b, v120
	v_exp_f32_e32 v98, v44
	s_waitcnt vmcnt(28)
	v_lshl_or_b32 v38, v139, 16, v137
	s_waitcnt vmcnt(25)
	v_lshl_or_b32 v39, v142, 16, v141
	s_waitcnt vmcnt(23)
	v_lshl_or_b32 v40, v118, 16, v143
	v_add_f32_e32 v118, v117, v136
	v_add_f32_e32 v127, v118, v138
	v_add_f32_e32 v129, v127, v140
	s_waitcnt vmcnt(22)
	v_add_f32_e32 v133, v129, v119
	s_waitcnt vmcnt(21)
	v_add_f32_e32 v135, v133, v144
	s_waitcnt vmcnt(20)
	v_add_f32_e32 v137, v135, v145
	s_waitcnt vmcnt(19)
	v_add_f32_e32 v139, v137, v146
	s_waitcnt vmcnt(18)
	v_add_f32_e32 v141, v139, v97
	ds_write_b32 v62, v141
	s_waitcnt lgkmcnt(0)
	s_barrier
	ds_read2st64_b32 v[42:43], v63 offset1:2
	ds_read2st64_b32 v[46:47], v63 offset0:4 offset1:6
	s_waitcnt vmcnt(16)
	v_lshl_or_b32 v41, v109, 16, v108
	s_waitcnt vmcnt(14)
	v_lshlrev_b32_e32 v99, 16, v148
	s_waitcnt lgkmcnt(1)
	v_add_f32_e32 v42, 0, v42
	v_cndmask_b32_e64 v44, v42, 0, s[8:9]
	v_add_f32_e32 v48, v43, v44
	v_cndmask_b32_e64 v44, v44, v48, s[10:11]
	v_add_f32_e32 v42, v42, v43
	s_waitcnt lgkmcnt(0)
	v_add_f32_e32 v43, v46, v44
	v_cndmask_b32_e64 v43, v44, v43, s[12:13]
	v_add_f32_e32 v44, v42, v46
	v_add_f32_e32 v42, v47, v43
	v_cndmask_b32_e64 v49, v43, v42, s[14:15]
	v_add_f32_e32 v43, v120, v49
	v_mov_b32_e32 v48, v47
	v_mul_f32_e32 v42, 0x3fb8aa3b, v43
	v_pk_add_f32 v[46:47], v[44:45], v[48:49]
	v_exp_f32_e32 v44, v42
	v_sub_f32_e32 v42, v46, v43
	v_mul_f32_e32 v43, 0xbfb8aa3b, v43
	v_exp_f32_e32 v48, v43
	v_mul_f32_e32 v43, 0x3fb8aa3b, v122
	v_mul_f32_e32 v44, v44, v99
	v_exp_f32_e32 v99, v43
	v_bfe_u32 v45, v44, 16, 1
	v_add3_u32 v44, v44, v45, s54
	ds_write_b16_d16_hi v72, v44
	v_pk_add_f32 v[44:45], v[98:99], 1.0 op_sel_hi:[1,0] neg_lo:[1,0] neg_hi:[1,0]
	v_sub_f32_e32 v43, v46, v47
	v_mul_f32_e32 v48, v44, v48
	v_mul_f32_e32 v42, 0x3fb8aa3b, v42
	v_mul_f32_e32 v43, 0x3fb8aa3b, v43
	v_bfe_u32 v98, v48, 16, 1
	v_exp_f32_e32 v42, v42
	v_exp_f32_e32 v43, v43
	v_add3_u32 v48, v48, v98, s54
	v_mul_f32_e32 v98, 0x3fb8aa3b, v47
	v_exp_f32_e32 v98, v98
	v_mul_f32_e32 v47, 0xbfb8aa3b, v47
	v_pk_mul_f32 v[42:43], v[44:45], v[42:43]
	v_lshlrev_b32_e32 v44, 16, v147
	v_exp_f32_e32 v47, v47
	v_mul_f32_e32 v44, v98, v44
	ds_write_b16_d16_hi v72, v48 offset:17408
	v_bfe_u32 v48, v44, 16, 1
	v_add3_u32 v44, v44, v48, s54
	v_cvt_pk_bf16_f32 v42, v42, v43
	v_add_f32_e32 v43, v100, v49
	ds_write_b16_d16_hi v73, v44 offset:272
	v_mul_f32_e32 v44, v45, v47
	v_mul_f32_e32 v47, 0x3fb8aa3b, v43
	v_bfe_u32 v45, v44, 16, 1
	v_exp_f32_e32 v47, v47
	v_add3_u32 v44, v44, v45, s54
	v_sub_f32_e32 v45, v46, v43
	v_mul_f32_e32 v45, 0x3fb8aa3b, v45
	v_exp_f32_e32 v98, v45
	s_waitcnt vmcnt(1)
	v_lshlrev_b32_e32 v45, 16, v101
	v_mul_f32_e32 v45, v47, v45
	v_bfe_u32 v47, v45, 16, 1
	v_add3_u32 v45, v45, v47, s54
	ds_write_b16_d16_hi v73, v44 offset:17680
	v_mul_f32_e32 v44, 0x3fb8aa3b, v124
	ds_write_b16_d16_hi v73, v45 offset:544
	v_mul_f32_e32 v45, 0x3fb8aa3b, v126
	v_exp_f32_e32 v44, v44
	v_mul_f32_e32 v43, 0xbfb8aa3b, v43
	v_exp_f32_e32 v45, v45
	v_exp_f32_e32 v43, v43
	v_add_f32_e32 v47, v102, v49
	v_sub_f32_e32 v48, v46, v47
	v_pk_add_f32 v[44:45], v[44:45], 1.0 op_sel_hi:[1,0] neg_lo:[1,0] neg_hi:[1,0]
	v_mul_f32_e32 v48, 0x3fb8aa3b, v48
	v_mul_f32_e32 v43, v44, v43
	v_exp_f32_e32 v99, v48
	v_bfe_u32 v48, v43, 16, 1
	v_add3_u32 v43, v43, v48, s54
	v_mul_f32_e32 v48, 0x3fb8aa3b, v47
	v_exp_f32_e32 v48, v48
	v_pk_mul_f32 v[98:99], v[44:45], v[98:99]
	v_mul_f32_e32 v44, 0xbfb8aa3b, v47
	ds_write_b16_d16_hi v73, v43 offset:17952
	v_lshlrev_b32_e32 v43, 16, v123
	v_exp_f32_e32 v44, v44
	v_mul_f32_e32 v43, v48, v43
	v_bfe_u32 v47, v43, 16, 1
	v_add3_u32 v43, v43, v47, s54
	ds_write_b16_d16_hi v73, v43 offset:816
	v_mul_f32_e32 v43, v45, v44
	v_add_f32_e32 v45, v103, v49
	v_mul_f32_e32 v48, 0x3fb8aa3b, v45
	v_exp_f32_e32 v48, v48
	v_bfe_u32 v44, v43, 16, 1
	v_sub_f32_e32 v47, v46, v45
	v_add3_u32 v43, v43, v44, s54
	v_mul_f32_e32 v47, 0x3fb8aa3b, v47
	ds_write_b16_d16_hi v73, v43 offset:18224
	v_cvt_pk_bf16_f32 v43, v98, v99
	v_exp_f32_e32 v98, v47
	v_lshlrev_b32_e32 v47, 16, v121
	v_mul_f32_e32 v47, v48, v47
; __device__ __forceinline__ unsigned f2bf(float f) { unsigned u = __builtin_bit_cast(unsigned, f); return (u + 0x7fffu + ((u >> 16) & 1u)) >> 16; }
; __device__ __forceinline__ unsigned pk2(float lo, float hi) { return pg8::cvt_pk_bf16(lo, hi); }
; __device__ __forceinline__ float ex2(float x) { return __builtin_amdgcn_exp2f(x); }
; template <bool OUT>
; __device__ __forceinline__ void hgrn_unit(int unit, LAS unsigned char* lds, const float* HLF, const bf16* HQ, const bf16* HV, const bf16* HG, bf16* MIX, float* UBUF, float* DTOT, const float* SST, gu32* rdy4 = nullptr) {
;     ...
;         for (int i = 0; i < 16; i += 2) {
;             float ke[2];
; #pragma unroll
;             for (int e = 0; e < 2; ++e) { const float bi = off + cs[i + e], kk = 1.0f - ex2(lf[i + e] * LOG2E_F); ke[e] = kk * ex2((blast - bi) * LOG2E_F);
;                 if (OUT) { QT[(16 * tq + i + e) * 136 + kx] = (bf16)f2bf(bf2f(qq[i + e]) * ex2(bi * LOG2E_F)); KI[(16 * tq + i + e) * 136 + kx] = (bf16)f2bf(kk * ex2(-bi * LOG2E_F)); } }
;             kew[i >> 1] = pk2(ke[0], ke[1]); vtw[i >> 1] = (unsigned)vv[i] | ((unsigned)vv[i + 1] << 16);
	v_bfe_u32 v48, v47, 16, 1
	v_add3_u32 v47, v47, v48, s54
	v_mul_f32_e32 v45, 0xbfb8aa3b, v45
	v_mul_f32_e32 v44, 0x3fb8aa3b, v128
	ds_write_b16_d16_hi v73, v47 offset:1088
	v_exp_f32_e32 v47, v45
	v_mul_f32_e32 v45, 0x3fb8aa3b, v130
	v_exp_f32_e32 v44, v44
	v_exp_f32_e32 v45, v45
	v_add_f32_e32 v48, v115, v49
	v_sub_f32_e32 v99, v46, v48
	v_mul_f32_e32 v99, 0x3fb8aa3b, v99
	v_pk_add_f32 v[44:45], v[44:45], 1.0 op_sel_hi:[1,0] neg_lo:[1,0] neg_hi:[1,0]
	v_exp_f32_e32 v99, v99
	v_mul_f32_e32 v47, v44, v47
	v_bfe_u32 v100, v47, 16, 1
	v_add3_u32 v47, v47, v100, s54
	v_mul_f32_e32 v100, 0x3fb8aa3b, v48
	v_exp_f32_e32 v100, v100
	ds_write_b16_d16_hi v73, v47 offset:18496
	v_mul_f32_e32 v47, 0xbfb8aa3b, v48
	v_pk_mul_f32 v[98:99], v[44:45], v[98:99]
	v_lshlrev_b32_e32 v44, 16, v125
	v_exp_f32_e32 v47, v47
	v_mul_f32_e32 v44, v100, v44
	v_bfe_u32 v48, v44, 16, 1
	v_add3_u32 v44, v44, v48, s54
	ds_write_b16_d16_hi v73, v44 offset:1360
	v_mul_f32_e32 v44, v45, v47
	v_bfe_u32 v45, v44, 16, 1
	v_add3_u32 v44, v44, v45, s54
	v_add_f32_e32 v45, v116, v49
	v_mul_f32_e32 v48, 0x3fb8aa3b, v45
	v_mul_f32_e32 v47, 0x3fb8aa3b, v132
	v_exp_f32_e32 v48, v48
	ds_write_b16_d16_hi v73, v44 offset:18768
	v_cvt_pk_bf16_f32 v44, v98, v99
	v_exp_f32_e32 v98, v47
	v_sub_f32_e32 v47, v46, v45
	v_mul_f32_e32 v47, 0x3fb8aa3b, v47
	v_exp_f32_e32 v100, v47
	v_lshlrev_b32_e32 v47, 16, v105
	v_mul_f32_e32 v47, v48, v47
	v_bfe_u32 v48, v47, 16, 1
	v_add3_u32 v47, v47, v48, s54
	v_mul_f32_e32 v48, 0x3fb8aa3b, v134
	v_mul_f32_e32 v45, 0xbfb8aa3b, v45
	v_exp_f32_e32 v99, v48
	v_exp_f32_e32 v45, v45
	ds_write_b16_d16_hi v73, v47 offset:1632
	v_add_f32_e32 v47, v117, v49
	v_sub_f32_e32 v48, v46, v47
	v_pk_add_f32 v[98:99], v[98:99], 1.0 op_sel_hi:[1,0] neg_lo:[1,0] neg_hi:[1,0]
	v_mul_f32_e32 v48, 0x3fb8aa3b, v48
	v_mul_f32_e32 v45, v98, v45
	v_exp_f32_e32 v101, v48
	v_bfe_u32 v48, v45, 16, 1
	v_add3_u32 v45, v45, v48, s54
	v_mul_f32_e32 v48, 0x3fb8aa3b, v47
	v_exp_f32_e32 v48, v48
	v_mul_f32_e32 v47, 0xbfb8aa3b, v47
	ds_write_b16_d16_hi v73, v45 offset:19040
	v_lshlrev_b32_e32 v45, 16, v104
	v_exp_f32_e32 v47, v47
	v_mul_f32_e32 v45, v48, v45
	v_bfe_u32 v48, v45, 16, 1
	v_add3_u32 v45, v45, v48, s54
	ds_write_b16_d16_hi v73, v45 offset:1904
	v_mul_f32_e32 v45, v99, v47
	v_bfe_u32 v47, v45, 16, 1
	v_add3_u32 v45, v45, v47, s54
	v_add_f32_e32 v47, v118, v49
	v_pk_mul_f32 v[100:101], v[98:99], v[100:101]
	v_mul_f32_e32 v99, 0x3fb8aa3b, v47
	v_mul_f32_e32 v48, 0x3fb8aa3b, v136
	v_exp_f32_e32 v99, v99
	v_exp_f32_e32 v98, v48
	v_sub_f32_e32 v48, v46, v47
	v_mul_f32_e32 v48, 0x3fb8aa3b, v48
	ds_write_b16_d16_hi v73, v45 offset:19312
	v_cvt_pk_bf16_f32 v45, v100, v101
	v_exp_f32_e32 v100, v48
	v_lshlrev_b32_e32 v48, 16, v107
	v_mul_f32_e32 v48, v99, v48
	v_bfe_u32 v99, v48, 16, 1
	v_add3_u32 v48, v48, v99, s54
	v_mul_f32_e32 v99, 0x3fb8aa3b, v138
	v_mul_f32_e32 v47, 0xbfb8aa3b, v47
	v_exp_f32_e32 v99, v99
	v_exp_f32_e32 v47, v47
	ds_write_b16_d16_hi v73, v48 offset:2176
	v_add_f32_e32 v48, v127, v49
	v_pk_add_f32 v[98:99], v[98:99], 1.0 op_sel_hi:[1,0] neg_lo:[1,0] neg_hi:[1,0]
	v_sub_f32_e32 v101, v46, v48
	v_mul_f32_e32 v47, v98, v47
	v_bfe_u32 v102, v47, 16, 1
	v_add3_u32 v47, v47, v102, s54
	v_mul_f32_e32 v102, 0x3fb8aa3b, v48
	v_mul_f32_e32 v101, 0x3fb8aa3b, v101
	v_exp_f32_e32 v102, v102
	v_exp_f32_e32 v101, v101
	v_mul_f32_e32 v48, 0xbfb8aa3b, v48
	ds_write_b16_d16_hi v73, v47 offset:19584
	v_lshlrev_b32_e32 v47, 16, v106
	v_exp_f32_e32 v48, v48
	v_mul_f32_e32 v47, v102, v47
	v_pk_mul_f32 v[100:101], v[98:99], v[100:101]
	v_bfe_u32 v98, v47, 16, 1
	v_add3_u32 v47, v47, v98, s54
	ds_write_b16_d16_hi v73, v47 offset:2448
	v_mul_f32_e32 v47, v99, v48
	v_bfe_u32 v48, v47, 16, 1
	v_add3_u32 v47, v47, v48, s54
	ds_write_b16_d16_hi v73, v47 offset:19856
	v_add_f32_e32 v47, v129, v49
	v_mul_f32_e32 v99, 0x3fb8aa3b, v47
	v_mul_f32_e32 v48, 0x3fb8aa3b, v140
	v_exp_f32_e32 v99, v99
	v_cvt_pk_bf16_f32 v98, v100, v101
	v_exp_f32_e32 v100, v48
	v_sub_f32_e32 v48, v46, v47
	v_mul_f32_e32 v48, 0x3fb8aa3b, v48
	v_exp_f32_e32 v102, v48
	s_waitcnt vmcnt(0)
; #define LAS __attribute__((address_space(3)))
; __device__ __forceinline__ unsigned f2bf(float f) { unsigned u = __builtin_bit_cast(unsigned, f); return (u + 0x7fffu + ((u >> 16) & 1u)) >> 16; }
; __device__ __forceinline__ unsigned pk2(float lo, float hi) { return pg8::cvt_pk_bf16(lo, hi); }
; __device__ __forceinline__ float ex2(float x) { return __builtin_amdgcn_exp2f(x); }
; template <bool OUT>
; __device__ __forceinline__ void hgrn_unit(int unit, LAS unsigned char* lds, const float* HLF, const bf16* HQ, const bf16* HV, const bf16* HG, bf16* MIX, float* UBUF, float* DTOT, const float* SST, gu32* rdy4 = nullptr) {
;     ...
;         for (int i = 0; i < 16; i += 2) {
;             float ke[2];
; #pragma unroll
;             for (int e = 0; e < 2; ++e) { const float bi = off + cs[i + e], kk = 1.0f - ex2(lf[i + e] * LOG2E_F); ke[e] = kk * ex2((blast - bi) * LOG2E_F);
;                 if (OUT) { QT[(16 * tq + i + e) * 136 + kx] = (bf16)f2bf(bf2f(qq[i + e]) * ex2(bi * LOG2E_F)); KI[(16 * tq + i + e) * 136 + kx] = (bf16)f2bf(kk * ex2(-bi * LOG2E_F)); } }
;             kew[i >> 1] = pk2(ke[0], ke[1]); vtw[i >> 1] = (unsigned)vv[i] | ((unsigned)vv[i + 1] << 16);
;         }
;         *(LAS v4u*)(KET + kx * 72 + 16 * tq) = (v4u){kew[0], kew[1], kew[2], kew[3]}; *(LAS v4u*)(KET + kx * 72 + 16 * tq + 8) = (v4u){kew[4], kew[5], kew[6], kew[7]};
;         *(LAS v4u*)(VT + kx * 72 + 16 * tq) = (v4u){vtw[0], vtw[1], vtw[2], vtw[3]}; *(LAS v4u*)(VT + kx * 72 + 16 * tq + 8) = (v4u){vtw[4], vtw[5], vtw[6], vtw[7]};
;         if (tq == 0) { DEC[kx] = ex2(blast * LOG2E_F); dacc += blast; }
;     ...
;             const v4u g0 = *(const v4u*)(HG + (size_t)row * 512 + col0 + 16 * seg), g1 = *(const v4u*)(HG + (size_t)row * 512 + col0 + 16 * seg + 8);
	v_add_u32_e32 v208, s58, v81
	v_ashrrev_i32_e32 v209, 31, v208
	v_lshlrev_b64 v[208:209], 10, v[208:209]
	v_lshl_add_u64 v[208:209], v[60:61], 0, v[208:209]
	global_load_dwordx4 v[200:203], v[208:209], off
	global_load_dwordx4 v[204:207], v[208:209], off offset:16
	v_lshlrev_b32_e32 v48, 16, v131
	v_mul_f32_e32 v48, v99, v48
	v_bfe_u32 v99, v48, 16, 1
	v_add3_u32 v48, v48, v99, s54
	v_mul_f32_e32 v99, 0x3fb8aa3b, v119
	v_mul_f32_e32 v47, 0xbfb8aa3b, v47
	v_exp_f32_e32 v101, v99
	v_exp_f32_e32 v47, v47
	ds_write_b16_d16_hi v73, v48 offset:2720
	v_add_f32_e32 v48, v133, v49
	v_sub_f32_e32 v99, v46, v48
	v_pk_add_f32 v[100:101], v[100:101], 1.0 op_sel_hi:[1,0] neg_lo:[1,0] neg_hi:[1,0]
	v_mul_f32_e32 v99, 0x3fb8aa3b, v99
	v_mul_f32_e32 v47, v100, v47
	v_exp_f32_e32 v103, v99
	v_bfe_u32 v99, v47, 16, 1
	v_add3_u32 v47, v47, v99, s54
	v_mul_f32_e32 v99, 0x3fb8aa3b, v48
	v_exp_f32_e32 v99, v99
	v_mul_f32_e32 v48, 0xbfb8aa3b, v48
	ds_write_b16_d16_hi v73, v47 offset:20128
	v_lshlrev_b32_e32 v47, 16, v113
	v_exp_f32_e32 v48, v48
	v_mul_f32_e32 v47, v99, v47
	v_bfe_u32 v99, v47, 16, 1
	v_add3_u32 v47, v47, v99, s54
	ds_write_b16_d16_hi v73, v47 offset:2992
	v_mul_f32_e32 v47, v101, v48
	v_bfe_u32 v48, v47, 16, 1
	v_add3_u32 v47, v47, v48, s54
	ds_write_b16_d16_hi v73, v47 offset:20400
	v_add_f32_e32 v47, v135, v49
	v_pk_mul_f32 v[102:103], v[100:101], v[102:103]
	v_mul_f32_e32 v101, 0x3fb8aa3b, v47
	v_mul_f32_e32 v48, 0x3fb8aa3b, v144
	v_exp_f32_e32 v101, v101
	v_exp_f32_e32 v100, v48
	v_sub_f32_e32 v48, v46, v47
	v_mul_f32_e32 v48, 0x3fb8aa3b, v48
	v_cvt_pk_bf16_f32 v99, v102, v103
	v_exp_f32_e32 v102, v48
	v_lshlrev_b32_e32 v48, 16, v112
	v_mul_f32_e32 v48, v101, v48
	v_bfe_u32 v101, v48, 16, 1
	v_add3_u32 v48, v48, v101, s54
	v_mul_f32_e32 v101, 0x3fb8aa3b, v145
	v_mul_f32_e32 v47, 0xbfb8aa3b, v47
	v_exp_f32_e32 v101, v101
	v_exp_f32_e32 v47, v47
	ds_write_b16_d16_hi v73, v48 offset:3264
	v_add_f32_e32 v48, v137, v49
	v_pk_add_f32 v[100:101], v[100:101], 1.0 op_sel_hi:[1,0] neg_lo:[1,0] neg_hi:[1,0]
	v_sub_f32_e32 v103, v46, v48
	v_mul_f32_e32 v47, v100, v47
	v_bfe_u32 v104, v47, 16, 1
	v_add3_u32 v47, v47, v104, s54
	v_mul_f32_e32 v104, 0x3fb8aa3b, v48
	v_mul_f32_e32 v103, 0x3fb8aa3b, v103
	v_exp_f32_e32 v104, v104
	v_exp_f32_e32 v103, v103
	v_mul_f32_e32 v48, 0xbfb8aa3b, v48
	ds_write_b16_d16_hi v73, v47 offset:20672
	v_lshlrev_b32_e32 v47, 16, v114
	v_exp_f32_e32 v48, v48
	v_mul_f32_e32 v47, v104, v47
	v_pk_mul_f32 v[102:103], v[100:101], v[102:103]
	v_bfe_u32 v100, v47, 16, 1
	v_add3_u32 v47, v47, v100, s54
	ds_write_b16_d16_hi v73, v47 offset:3536
	v_mul_f32_e32 v47, v101, v48
	v_bfe_u32 v48, v47, 16, 1
	v_add3_u32 v47, v47, v48, s54
	ds_write_b16_d16_hi v73, v47 offset:20944
	v_add_f32_e32 v47, v139, v49
	v_cvt_pk_bf16_f32 v100, v102, v103
	v_mul_f32_e32 v102, 0x3fb8aa3b, v47
	v_exp_f32_e32 v103, v102
	v_sub_f32_e32 v101, v46, v47
	v_mul_f32_e32 v101, 0x3fb8aa3b, v101
	v_exp_f32_e32 v102, v101
	v_lshlrev_b32_e32 v101, 16, v111
	v_mul_f32_e32 v101, v103, v101
	v_bfe_u32 v103, v101, 16, 1
	v_add3_u32 v101, v101, v103, s54
	v_mul_f32_e32 v48, 0x3fb8aa3b, v146
	ds_write_b16_d16_hi v73, v101 offset:3808
	v_add_f32_e32 v101, v141, v49
	v_mul_f32_e32 v49, 0x3fb8aa3b, v97
	v_exp_f32_e32 v48, v48
	v_mul_f32_e32 v47, 0xbfb8aa3b, v47
	v_exp_f32_e32 v49, v49
	v_exp_f32_e32 v47, v47
	v_sub_f32_e32 v97, v46, v101
	v_mul_f32_e32 v97, 0x3fb8aa3b, v97
	v_pk_add_f32 v[48:49], v[48:49], 1.0 op_sel_hi:[1,0] neg_lo:[1,0] neg_hi:[1,0]
	v_exp_f32_e32 v103, v97
	v_mul_f32_e32 v47, v48, v47
	v_bfe_u32 v97, v47, 16, 1
	v_add3_u32 v47, v47, v97, s54
	v_mul_f32_e32 v97, 0x3fb8aa3b, v101
	v_exp_f32_e32 v97, v97
	v_pk_mul_f32 v[102:103], v[48:49], v[102:103]
	v_mul_f32_e32 v48, 0xbfb8aa3b, v101
	ds_write_b16_d16_hi v73, v47 offset:21216
	v_lshlrev_b32_e32 v47, 16, v110
	v_exp_f32_e32 v48, v48
	v_mul_f32_e32 v47, v97, v47
	v_bfe_u32 v97, v47, 16, 1
	v_add3_u32 v47, v47, v97, s54
	ds_write_b16_d16_hi v74, v47
	v_mul_f32_e32 v47, v49, v48
	v_bfe_u32 v48, v47, 16, 1
	v_add3_u32 v47, v47, v48, s54
	ds_write_b16_d16_hi v74, v47 offset:17408
	v_cvt_pk_bf16_f32 v101, v102, v103
	ds_write_b128 v64, v[42:45] offset:34816
	ds_write_b128 v64, v[98:101] offset:34832
	ds_write_b128 v64, v[34:37] offset:53248
	ds_write_b128 v64, v[38:41] offset:53264
	s_and_saveexec_b64 s[82:83], s[8:9]
	s_cbranch_execz .LBB0_588
	v_mul_f32_e32 v34, 0x3fb8aa3b, v46
	v_exp_f32_e32 v34, v34
	ds_write_b32 v65, v34
